# with the K-blocked ACT, P7's per-XCC weight-block rotation is 2*xcc (eight distinct starting blocks) instead of 4*(xcc&3)
# baseline (speedup 1.0000x reference)
;     __device__ __forceinline__ void tile(int L, int& pm, int& pn) const {
;         const unsigned w = (unsigned)(L & 7) * (2u * fnig) + (unsigned)(L >> 3), gid = __umulhi(w, fmagic), rem = w - gid * fnig; pm = (int)(gid * WGM + (rem & 7u)); pn = (int)(rem >> 3);
;     }
; __global__ void __launch_bounds__(512, 2) layer_fwd(Args args) {
;     ...
;     if (IN(7)) {
;         pg8::Sched S; S.A0 = (const char*)(ws + WS_HB); S.B0 = (const char*)(ws + WS_WUP); S.A1 = S.A0; S.B1 = S.B0;
;         S.nM0 = M / 256; S.nN0 = 16; S.n0 = S.nM0 * 16; S.n1 = 0; S.G = F.G; S.c = vb_; S.tstep = (size_t)256 * D * 2; S.nrep = NREP(7); S.prep();
;         pg8::EpiScale<1> E{(bf16_t*)(ws + WS_ACT), FF, ss3};
;         pg8::gemm_phase<pg8::EpiScale<1>, true, true>(F.lds, D, S, E);
;     }
.LBB0_1078:
	s_cmp_lt_i32 s82, 8
	s_cselect_b64 s[6:7], -1, 0
	s_and_b64 s[2:3], s[6:7], s[2:3]
	s_andn2_b64 vcc, exec, s[2:3]
	s_cbranch_vccnz .LBB0_1095
	s_cmpk_gt_i32 s52, 0x7ff
	v_readfirstlane_b32 s16, v228
	s_cbranch_scc1 .LBB0_1095
	v_lshrrev_b32_e32 v0, 5, v228
	v_lshrrev_b32_e32 v2, 1, v228
	v_and_b32_e32 v0, 4, v0
	s_waitcnt lgkmcnt(0)
	v_bfe_u32 v1, v228, 2, 2
	v_and_b32_e32 v2, 24, v2
	v_or3_b32 v0, v0, v1, v2
	v_lshlrev_b32_e32 v1, 4, v228
	v_add_u32_e32 v8, 0x2000, v1
	v_lshrrev_b32_e32 v2, 7, v8
	s_movk_i32 s6, 0xe0
	v_and_b32_e32 v4, 32, v228
	v_and_or_b32 v3, v2, s6, v0
	v_bitop3_b32 v9, v1, v4, 48 bitop3:0x6c
	v_and_b32_e32 v10, 64, v228
	v_bfe_u32 v11, v228, 2, 4
	s_movk_i32 s6, 0xf0
	s_add_u32 s48, s92, 0x3000000
	v_or_b32_e32 v1, v9, v10
	v_and_or_b32 v2, v2, s6, v11
	s_addc_u32 s49, s93, 0
	v_lshl_or_b32 v130, v2, 11, v1
	v_lshrrev_b32_e32 v2, 3, v228
	s_movk_i32 s6, 0x60
	s_add_u32 s50, s92, 0xd80000
	v_and_or_b32 v0, v2, s6, v0
	s_movk_i32 s6, 0x70
	s_addc_u32 s51, s93, 0
	v_lshl_or_b32 v132, v0, 11, v1
	v_and_or_b32 v0, v2, s6, v11
	s_lshl_b32 s6, s52, 8
	s_and_b32 s6, s6, 0x700
	s_ashr_i32 s7, s52, 3
	s_add_i32 s6, s6, s7
	s_lshr_b32 s6, s6, 4
	s_and_b32 s6, s6, 0xffffff8
	s_and_b32 s8, s7, 7
	s_lshr_b32 s14, s16, 6
	s_or_b32 s6, s6, s8
	s_xor_b32 s6, s6, 8
	s_bfe_u32 s71, s7, 0x40003
	s_and_b32 s98, s52, 7
	s_lshl_b32 s98, s98, 1
	s_add_i32 s71, s71, s98
	s_and_b32 s71, s71, 15
	s_mov_b32 s7, 0
	s_lshr_b32 s15, s16, 8
	s_lshl_b32 s53, s14, 10
	s_lshl_b64 s[8:9], s[6:7], 19
	s_lshl_b32 s10, s71, 19
	s_add_u32 s44, s50, s10
	s_addc_u32 s45, s51, 0
	s_add_i32 s54, s53, 0
	s_add_i32 m0, s54, 0x10000
	v_lshl_or_b32 v128, v3, 11, v1
	global_load_lds_dwordx4 v132, s[44:45]
	s_add_i32 m0, s54, 0x12000
	s_add_u32 s10, s44, 0x40000
	global_load_lds_dwordx4 v128, s[44:45]
	s_addc_u32 s11, s45, 0
	s_add_i32 m0, s54, 0x14000
	v_lshl_or_b32 v134, v0, 11, v1
	global_load_lds_dwordx4 v132, s[10:11]
	s_add_i32 m0, s54, 0x16000
	s_add_u32 s42, s48, s8
	s_addc_u32 s43, s49, s9
	s_add_i32 s55, s54, 0x2000
	global_load_lds_dwordx4 v128, s[10:11]
	s_mov_b32 m0, s54
	s_add_u32 s8, s42, 0x40000
	global_load_lds_dwordx4 v134, s[42:43]
	s_mov_b32 m0, s55
	s_addc_u32 s9, s43, 0
	s_add_i32 s56, s54, 0x4000
	global_load_lds_dwordx4 v130, s[42:43]
	s_mov_b32 m0, s56
	s_add_i32 s57, s54, 0x6000
	global_load_lds_dwordx4 v134, s[8:9]
	s_mov_b32 m0, s57
	v_mov_b32_e32 v133, 0
	global_load_lds_dwordx4 v130, s[8:9]
	v_mov_b32_e32 v129, v133
	v_mov_b32_e32 v135, v133
	v_mov_b32_e32 v131, v133
	s_cmp_eq_u32 s15, 1
	v_lshl_add_u64 v[6:7], s[44:45], 0, v[132:133]
	v_lshl_add_u64 v[2:3], s[44:45], 0, v[128:129]
	s_mov_b64 s[8:9], 0x40000
	v_lshl_add_u64 v[0:1], s[42:43], 0, v[134:135]
	s_cselect_b64 s[10:11], -1, 0
	s_cmp_lg_u32 s15, 1
	v_lshl_add_u64 v[4:5], s[42:43], 0, v[130:131]
	s_cbranch_scc1 .LBB0_1082
	s_barrier

;     __device__ __forceinline__ void tile(int L, int& pm, int& pn) const {
;         const unsigned w = (unsigned)(L & 7) * (2u * fnig) + (unsigned)(L >> 3), gid = __umulhi(w, fmagic), rem = w - gid * fnig; pm = (int)(gid * WGM + (rem & 7u)); pn = (int)(rem >> 3);
;     }
;     __device__ __forceinline__ bool next(int i, Unit& u) const {
;         int L = i * G + c;
;         if (nrep > 1) { if (L < n0 * nrep) { const int pass = L / n0; tile(L - pass * n0, u.pm, u.pn); u.kind = (pass + 1 < nrep) ? 2 : 0; return true; } L -= n0 * (nrep - 1); }
;         if (L < n0) { tile(L, u.pm, u.pn); u.pn += pnoff; u.kind = 0; return true; }
.LBB0_1085:
	s_add_i32 s7, s7, 1
	s_mul_i32 s31, s7, s33
	s_add_i32 s31, s31, s52
	s_cmpk_lt_i32 s31, 0x800
	s_cselect_b64 s[38:39], -1, 0
	s_cmpk_gt_i32 s31, 0x7ff
	s_cbranch_scc1 .LBB0_1087
	s_lshl_b32 s30, s31, 8
	s_and_b32 s30, s30, 0x700
	s_ashr_i32 s31, s31, 3
	s_add_i32 s30, s30, s31
	s_lshr_b32 s30, s30, 4
	s_and_b32 s30, s30, 0xffffff8
	s_and_b32 s34, s31, 7
	s_or_b32 s30, s30, s34
	s_xor_b32 s30, s30, 8
	s_bfe_u32 s34, s31, 0x40003
	s_and_b32 s98, s52, 7
	s_lshl_b32 s98, s98, 1
	s_add_i32 s34, s34, s98
	s_and_b32 s34, s34, 15
